# static priority raise for the older half instead: per-burst s_setprio pairs deleted, waves 0..3 at s_setprio 1 (0 inside P7)
# speedup vs baseline: 1.0086x; 1.0086x over previous
; #define LAS __attribute__((address_space(3)))
; __global__ void __launch_bounds__(NTHR, 2) mega(Args args) {
;     extern __shared__ __attribute__((aligned(16))) unsigned char lds_raw[];
;     LAS unsigned char* lds = (LAS unsigned char*)lds_raw;
;     cg::grid_group grid = cg::this_grid();
;     const int G = gridDim.x, bx = blockIdx.x;
_Z4mega4Args:
	s_load_dwordx2 s[34:35], s[0:1], 0x140
	s_load_dword s33, s[0:1], 0x150
	s_add_u32 s4, s0, 0x150
	v_and_b32_e32 v202, 0x3ff, v0
	s_mov_b32 s81, s2
	s_addc_u32 s5, s1, 0
	v_readfirstlane_b32 s98, v202
	s_nop 3
	s_bfe_u32 s98, s98, 0x40006
	s_cmp_lt_u32 s98, 4
	s_cbranch_scc0 .Lprio_static_a
	s_setprio 1

; #define RUN(k) if (lo <= (k) && (k) < hi) { if ((k) == DUPK) { run_phase<k>(args, lds, G, bx, false); GSYNC(); } run_phase<k>(args, lds, G, bx); if ((k) + 1 < hi) GSYNC(); }
; __global__ void __launch_bounds__(NTHR, 2) mega(Args args) {
;     ...
;     RUN(0) RUN(1) RUN(2) RUN(4) RUN(5) RUN(6) RUN(7) RUN(8) RUN(9) RUN(11) RUN(12) RUN(14) RUN(16) RUN(17)
.LBB0_1083:
	v_readfirstlane_b32 s98, v202
	s_nop 3
	s_bfe_u32 s98, s98, 0x40006
	s_cmp_lt_u32 s98, 4
	s_cbranch_scc0 .Lprio_static_b
	s_setprio 1
